# stagger g x ~5.2 us (1.5x)
# speedup vs baseline: 1.0149x; 1.0149x over previous
; __device__ __forceinline__ void xcd_barrier(const XcdBarrier& b) {
;     ...
;     __syncthreads();
; __global__ void __launch_bounds__(NWAVES * 64, 2) fwd_kernel(Args args) {
;     ...
;         if (ph + 1 < args.ph_hi || rep + 1 < nrep) { if (args.ph_hi > 1000) grid.sync(); else xcd_barrier(xb); } else __syncthreads();
.LBB0_486:
	s_or_b64 exec, exec, s[26:27]
	s_cmp_eq_u32 s10, 1
	s_cbranch_scc0 stg_skip
	s_and_b32 s2, s89, 7
	s_mul_i32 s2, s2, 3
